# adds: band epilogue gate loads issued before the last loop barrier
# speedup vs baseline: 1.0195x; 1.0067x over previous
.Lband_epi_compute:
	v_rcp_f32_e32 v118, v126
	v_rcp_f32_e32 v119, v34
	s_nop 0
	v_fma_f32 v0, -v126, v118, 1.0
	v_fma_f32 v120, -v34, v119, 1.0
	v_fmac_f32_e32 v118, v0, v118
	v_fmac_f32_e32 v119, v120, v119
	v_mov_b32_e32 v0, v118
	v_mov_b32_e32 v120, v119
	s_waitcnt vmcnt(15)
	v_lshlrev_b32_e32 v66, 16, v86
	v_and_b32_e32 v67, 0xffff0000, v86
	v_lshlrev_b32_e32 v68, 16, v87
	v_and_b32_e32 v69, 0xffff0000, v87
	v_mul_f32_e32 v70, 0xbfb8aa3b, v66
	v_mul_f32_e32 v71, 0xbfb8aa3b, v67
	v_mul_f32_e32 v72, 0xbfb8aa3b, v68
	v_mul_f32_e32 v73, 0xbfb8aa3b, v69
	v_exp_f32_e32 v70, v70
	v_exp_f32_e32 v71, v71
	v_exp_f32_e32 v72, v72
	v_exp_f32_e32 v73, v73
	v_pk_mul_f32 v[78:79], v[82:83], v[0:1] op_sel_hi:[1,0]
	v_pk_add_f32 v[70:71], v[70:71], 1.0 op_sel_hi:[1,0]
	v_pk_add_f32 v[72:73], v[72:73], 1.0 op_sel_hi:[1,0]
	v_rcp_f32_e32 v74, v70
	v_rcp_f32_e32 v75, v71
	v_rcp_f32_e32 v76, v72
	v_rcp_f32_e32 v77, v73
	v_pk_mul_f32 v[80:81], v[84:85], v[0:1] op_sel_hi:[1,0]
	v_pk_mul_f32 v[74:75], v[66:67], v[74:75]
	v_pk_mul_f32 v[76:77], v[68:69], v[76:77]
	v_pk_mul_f32 v[78:79], v[78:79], v[74:75]
	v_pk_mul_f32 v[80:81], v[80:81], v[76:77]
	v_cvt_pk_bf16_f32 v70, v78, v79
	v_cvt_pk_bf16_f32 v71, v80, v81
	global_store_dwordx2 v124, v[70:71], s[38:39]
	s_waitcnt vmcnt(15)
	v_lshlrev_b32_e32 v66, 16, v88
	v_and_b32_e32 v67, 0xffff0000, v88
	v_lshlrev_b32_e32 v68, 16, v89
	v_and_b32_e32 v69, 0xffff0000, v89
	v_mul_f32_e32 v70, 0xbfb8aa3b, v66
	v_mul_f32_e32 v71, 0xbfb8aa3b, v67
	v_mul_f32_e32 v72, 0xbfb8aa3b, v68
	v_mul_f32_e32 v73, 0xbfb8aa3b, v69
	v_exp_f32_e32 v70, v70
	v_exp_f32_e32 v71, v71
	v_exp_f32_e32 v72, v72
	v_exp_f32_e32 v73, v73
	v_pk_mul_f32 v[78:79], v[62:63], v[0:1] op_sel_hi:[1,0]
	v_pk_add_f32 v[70:71], v[70:71], 1.0 op_sel_hi:[1,0]
	v_pk_add_f32 v[72:73], v[72:73], 1.0 op_sel_hi:[1,0]
	v_rcp_f32_e32 v74, v70
	v_rcp_f32_e32 v75, v71
	v_rcp_f32_e32 v76, v72
	v_rcp_f32_e32 v77, v73
	v_pk_mul_f32 v[80:81], v[64:65], v[0:1] op_sel_hi:[1,0]
	v_pk_mul_f32 v[74:75], v[66:67], v[74:75]
	v_pk_mul_f32 v[76:77], v[68:69], v[76:77]
	v_pk_mul_f32 v[78:79], v[78:79], v[74:75]
	v_pk_mul_f32 v[80:81], v[80:81], v[76:77]
	v_cvt_pk_bf16_f32 v70, v78, v79
	v_cvt_pk_bf16_f32 v71, v80, v81
	global_store_dwordx2 v124, v[70:71], s[38:39] offset:32
	s_waitcnt vmcnt(15)
	v_lshlrev_b32_e32 v66, 16, v90
	v_and_b32_e32 v67, 0xffff0000, v90
	v_lshlrev_b32_e32 v68, 16, v91
	v_and_b32_e32 v69, 0xffff0000, v91
	v_mul_f32_e32 v70, 0xbfb8aa3b, v66
	v_mul_f32_e32 v71, 0xbfb8aa3b, v67
	v_mul_f32_e32 v72, 0xbfb8aa3b, v68
	v_mul_f32_e32 v73, 0xbfb8aa3b, v69
	v_exp_f32_e32 v70, v70
	v_exp_f32_e32 v71, v71
	v_exp_f32_e32 v72, v72
	v_exp_f32_e32 v73, v73
	v_pk_mul_f32 v[78:79], v[58:59], v[0:1] op_sel_hi:[1,0]
	v_pk_add_f32 v[70:71], v[70:71], 1.0 op_sel_hi:[1,0]
	v_pk_add_f32 v[72:73], v[72:73], 1.0 op_sel_hi:[1,0]
	v_rcp_f32_e32 v74, v70
	v_rcp_f32_e32 v75, v71
	v_rcp_f32_e32 v76, v72
	v_rcp_f32_e32 v77, v73
	v_pk_mul_f32 v[80:81], v[60:61], v[0:1] op_sel_hi:[1,0]
	v_pk_mul_f32 v[74:75], v[66:67], v[74:75]
	v_pk_mul_f32 v[76:77], v[68:69], v[76:77]
	v_pk_mul_f32 v[78:79], v[78:79], v[74:75]
	v_pk_mul_f32 v[80:81], v[80:81], v[76:77]
	v_cvt_pk_bf16_f32 v70, v78, v79
	v_cvt_pk_bf16_f32 v71, v80, v81
	global_store_dwordx2 v124, v[70:71], s[38:39] offset:64
	s_waitcnt vmcnt(15)
	v_lshlrev_b32_e32 v66, 16, v92
	v_and_b32_e32 v67, 0xffff0000, v92
	v_lshlrev_b32_e32 v68, 16, v93
	v_and_b32_e32 v69, 0xffff0000, v93
	v_mul_f32_e32 v70, 0xbfb8aa3b, v66
	v_mul_f32_e32 v71, 0xbfb8aa3b, v67
	v_mul_f32_e32 v72, 0xbfb8aa3b, v68
	v_mul_f32_e32 v73, 0xbfb8aa3b, v69
	v_exp_f32_e32 v70, v70
	v_exp_f32_e32 v71, v71
	v_exp_f32_e32 v72, v72
	v_exp_f32_e32 v73, v73
	v_pk_mul_f32 v[78:79], v[54:55], v[0:1] op_sel_hi:[1,0]
	v_pk_add_f32 v[70:71], v[70:71], 1.0 op_sel_hi:[1,0]
	v_pk_add_f32 v[72:73], v[72:73], 1.0 op_sel_hi:[1,0]
	v_rcp_f32_e32 v74, v70
	v_rcp_f32_e32 v75, v71
	v_rcp_f32_e32 v76, v72
	v_rcp_f32_e32 v77, v73
	v_pk_mul_f32 v[80:81], v[56:57], v[0:1] op_sel_hi:[1,0]
	v_pk_mul_f32 v[74:75], v[66:67], v[74:75]
	v_pk_mul_f32 v[76:77], v[68:69], v[76:77]
	v_pk_mul_f32 v[78:79], v[78:79], v[74:75]
	v_pk_mul_f32 v[80:81], v[80:81], v[76:77]
	v_cvt_pk_bf16_f32 v70, v78, v79
	v_cvt_pk_bf16_f32 v71, v80, v81
	global_store_dwordx2 v124, v[70:71], s[38:39] offset:96
	s_waitcnt vmcnt(15)
	v_lshlrev_b32_e32 v66, 16, v94
	v_and_b32_e32 v67, 0xffff0000, v94
	v_lshlrev_b32_e32 v68, 16, v95
	v_and_b32_e32 v69, 0xffff0000, v95
	v_mul_f32_e32 v70, 0xbfb8aa3b, v66
	v_mul_f32_e32 v71, 0xbfb8aa3b, v67
	v_mul_f32_e32 v72, 0xbfb8aa3b, v68
	v_mul_f32_e32 v73, 0xbfb8aa3b, v69
	v_exp_f32_e32 v70, v70
	v_exp_f32_e32 v71, v71
	v_exp_f32_e32 v72, v72
	v_exp_f32_e32 v73, v73
	v_pk_mul_f32 v[78:79], v[50:51], v[0:1] op_sel_hi:[1,0]
	v_pk_add_f32 v[70:71], v[70:71], 1.0 op_sel_hi:[1,0]
	v_pk_add_f32 v[72:73], v[72:73], 1.0 op_sel_hi:[1,0]
	v_rcp_f32_e32 v74, v70
	v_rcp_f32_e32 v75, v71
	v_rcp_f32_e32 v76, v72
	v_rcp_f32_e32 v77, v73
	v_pk_mul_f32 v[80:81], v[52:53], v[0:1] op_sel_hi:[1,0]
	v_pk_mul_f32 v[74:75], v[66:67], v[74:75]
	v_pk_mul_f32 v[76:77], v[68:69], v[76:77]
	v_pk_mul_f32 v[78:79], v[78:79], v[74:75]
	v_pk_mul_f32 v[80:81], v[80:81], v[76:77]
	v_cvt_pk_bf16_f32 v70, v78, v79
	v_cvt_pk_bf16_f32 v71, v80, v81
	global_store_dwordx2 v124, v[70:71], s[38:39] offset:128
	s_waitcnt vmcnt(15)
	v_lshlrev_b32_e32 v66, 16, v96
	v_and_b32_e32 v67, 0xffff0000, v96
	v_lshlrev_b32_e32 v68, 16, v97
	v_and_b32_e32 v69, 0xffff0000, v97
	v_mul_f32_e32 v70, 0xbfb8aa3b, v66
	v_mul_f32_e32 v71, 0xbfb8aa3b, v67
	v_mul_f32_e32 v72, 0xbfb8aa3b, v68
	v_mul_f32_e32 v73, 0xbfb8aa3b, v69
	v_exp_f32_e32 v70, v70
	v_exp_f32_e32 v71, v71
	v_exp_f32_e32 v72, v72
	v_exp_f32_e32 v73, v73
	v_pk_mul_f32 v[78:79], v[46:47], v[0:1] op_sel_hi:[1,0]
	v_pk_add_f32 v[70:71], v[70:71], 1.0 op_sel_hi:[1,0]
	v_pk_add_f32 v[72:73], v[72:73], 1.0 op_sel_hi:[1,0]
	v_rcp_f32_e32 v74, v70
	v_rcp_f32_e32 v75, v71
	v_rcp_f32_e32 v76, v72
	v_rcp_f32_e32 v77, v73
	v_pk_mul_f32 v[80:81], v[48:49], v[0:1] op_sel_hi:[1,0]
	v_pk_mul_f32 v[74:75], v[66:67], v[74:75]
	v_pk_mul_f32 v[76:77], v[68:69], v[76:77]
	v_pk_mul_f32 v[78:79], v[78:79], v[74:75]
	v_pk_mul_f32 v[80:81], v[80:81], v[76:77]
	v_cvt_pk_bf16_f32 v70, v78, v79
	v_cvt_pk_bf16_f32 v71, v80, v81
	global_store_dwordx2 v124, v[70:71], s[38:39] offset:160
	s_waitcnt vmcnt(15)
	v_lshlrev_b32_e32 v66, 16, v98
	v_and_b32_e32 v67, 0xffff0000, v98
	v_lshlrev_b32_e32 v68, 16, v99
	v_and_b32_e32 v69, 0xffff0000, v99
	v_mul_f32_e32 v70, 0xbfb8aa3b, v66
	v_mul_f32_e32 v71, 0xbfb8aa3b, v67
	v_mul_f32_e32 v72, 0xbfb8aa3b, v68
	v_mul_f32_e32 v73, 0xbfb8aa3b, v69
	v_exp_f32_e32 v70, v70
	v_exp_f32_e32 v71, v71
	v_exp_f32_e32 v72, v72
	v_exp_f32_e32 v73, v73
	v_pk_mul_f32 v[78:79], v[42:43], v[0:1] op_sel_hi:[1,0]
	v_pk_add_f32 v[70:71], v[70:71], 1.0 op_sel_hi:[1,0]
	v_pk_add_f32 v[72:73], v[72:73], 1.0 op_sel_hi:[1,0]
	v_rcp_f32_e32 v74, v70
	v_rcp_f32_e32 v75, v71
	v_rcp_f32_e32 v76, v72
	v_rcp_f32_e32 v77, v73
	v_pk_mul_f32 v[80:81], v[44:45], v[0:1] op_sel_hi:[1,0]
	v_pk_mul_f32 v[74:75], v[66:67], v[74:75]
	v_pk_mul_f32 v[76:77], v[68:69], v[76:77]
	v_pk_mul_f32 v[78:79], v[78:79], v[74:75]
	v_pk_mul_f32 v[80:81], v[80:81], v[76:77]
	v_cvt_pk_bf16_f32 v70, v78, v79
	v_cvt_pk_bf16_f32 v71, v80, v81
	global_store_dwordx2 v124, v[70:71], s[38:39] offset:192
	s_waitcnt vmcnt(15)
	v_lshlrev_b32_e32 v66, 16, v100
	v_and_b32_e32 v67, 0xffff0000, v100
	v_lshlrev_b32_e32 v68, 16, v101
	v_and_b32_e32 v69, 0xffff0000, v101
	v_mul_f32_e32 v70, 0xbfb8aa3b, v66
	v_mul_f32_e32 v71, 0xbfb8aa3b, v67
	v_mul_f32_e32 v72, 0xbfb8aa3b, v68
	v_mul_f32_e32 v73, 0xbfb8aa3b, v69
	v_exp_f32_e32 v70, v70
	v_exp_f32_e32 v71, v71
	v_exp_f32_e32 v72, v72
	v_exp_f32_e32 v73, v73
	v_pk_mul_f32 v[78:79], v[38:39], v[0:1] op_sel_hi:[1,0]
	v_pk_add_f32 v[70:71], v[70:71], 1.0 op_sel_hi:[1,0]
	v_pk_add_f32 v[72:73], v[72:73], 1.0 op_sel_hi:[1,0]
	v_rcp_f32_e32 v74, v70
	v_rcp_f32_e32 v75, v71
	v_rcp_f32_e32 v76, v72
	v_rcp_f32_e32 v77, v73
	v_pk_mul_f32 v[80:81], v[40:41], v[0:1] op_sel_hi:[1,0]
	v_pk_mul_f32 v[74:75], v[66:67], v[74:75]
	v_pk_mul_f32 v[76:77], v[68:69], v[76:77]
	v_pk_mul_f32 v[78:79], v[78:79], v[74:75]
	v_pk_mul_f32 v[80:81], v[80:81], v[76:77]
	v_cvt_pk_bf16_f32 v70, v78, v79
	v_cvt_pk_bf16_f32 v71, v80, v81
	global_store_dwordx2 v124, v[70:71], s[38:39] offset:224
	s_waitcnt vmcnt(15)
	v_lshlrev_b32_e32 v66, 16, v102
	v_and_b32_e32 v67, 0xffff0000, v102
	v_lshlrev_b32_e32 v68, 16, v103
	v_and_b32_e32 v69, 0xffff0000, v103
	v_mul_f32_e32 v70, 0xbfb8aa3b, v66
	v_mul_f32_e32 v71, 0xbfb8aa3b, v67
	v_mul_f32_e32 v72, 0xbfb8aa3b, v68
	v_mul_f32_e32 v73, 0xbfb8aa3b, v69
	v_exp_f32_e32 v70, v70
	v_exp_f32_e32 v71, v71
	v_exp_f32_e32 v72, v72
	v_exp_f32_e32 v73, v73
	v_pk_mul_f32 v[78:79], v[30:31], v[120:121] op_sel_hi:[1,0]
	v_pk_add_f32 v[70:71], v[70:71], 1.0 op_sel_hi:[1,0]
	v_pk_add_f32 v[72:73], v[72:73], 1.0 op_sel_hi:[1,0]
	v_rcp_f32_e32 v74, v70
	v_rcp_f32_e32 v75, v71
	v_rcp_f32_e32 v76, v72
	v_rcp_f32_e32 v77, v73
	v_pk_mul_f32 v[80:81], v[32:33], v[120:121] op_sel_hi:[1,0]
	v_pk_mul_f32 v[74:75], v[66:67], v[74:75]
	v_pk_mul_f32 v[76:77], v[68:69], v[76:77]
	v_pk_mul_f32 v[78:79], v[78:79], v[74:75]
	v_pk_mul_f32 v[80:81], v[80:81], v[76:77]
	v_cvt_pk_bf16_f32 v70, v78, v79
	v_cvt_pk_bf16_f32 v71, v80, v81
	global_store_dwordx2 v125, v[70:71], s[38:39]
	s_waitcnt vmcnt(15)
	v_lshlrev_b32_e32 v66, 16, v104
	v_and_b32_e32 v67, 0xffff0000, v104
	v_lshlrev_b32_e32 v68, 16, v105
	v_and_b32_e32 v69, 0xffff0000, v105
	v_mul_f32_e32 v70, 0xbfb8aa3b, v66
	v_mul_f32_e32 v71, 0xbfb8aa3b, v67
	v_mul_f32_e32 v72, 0xbfb8aa3b, v68
	v_mul_f32_e32 v73, 0xbfb8aa3b, v69
	v_exp_f32_e32 v70, v70
	v_exp_f32_e32 v71, v71
	v_exp_f32_e32 v72, v72
	v_exp_f32_e32 v73, v73
	v_pk_mul_f32 v[78:79], v[26:27], v[120:121] op_sel_hi:[1,0]
	v_pk_add_f32 v[70:71], v[70:71], 1.0 op_sel_hi:[1,0]
	v_pk_add_f32 v[72:73], v[72:73], 1.0 op_sel_hi:[1,0]
	v_rcp_f32_e32 v74, v70
	v_rcp_f32_e32 v75, v71
	v_rcp_f32_e32 v76, v72
	v_rcp_f32_e32 v77, v73
	v_pk_mul_f32 v[80:81], v[28:29], v[120:121] op_sel_hi:[1,0]
	v_pk_mul_f32 v[74:75], v[66:67], v[74:75]
	v_pk_mul_f32 v[76:77], v[68:69], v[76:77]
	v_pk_mul_f32 v[78:79], v[78:79], v[74:75]
	v_pk_mul_f32 v[80:81], v[80:81], v[76:77]
	v_cvt_pk_bf16_f32 v70, v78, v79
	v_cvt_pk_bf16_f32 v71, v80, v81
	global_store_dwordx2 v125, v[70:71], s[38:39] offset:32
	s_waitcnt vmcnt(15)
	v_lshlrev_b32_e32 v66, 16, v106
	v_and_b32_e32 v67, 0xffff0000, v106
	v_lshlrev_b32_e32 v68, 16, v107
	v_and_b32_e32 v69, 0xffff0000, v107
	v_mul_f32_e32 v70, 0xbfb8aa3b, v66
	v_mul_f32_e32 v71, 0xbfb8aa3b, v67
	v_mul_f32_e32 v72, 0xbfb8aa3b, v68
	v_mul_f32_e32 v73, 0xbfb8aa3b, v69
	v_exp_f32_e32 v70, v70
	v_exp_f32_e32 v71, v71
	v_exp_f32_e32 v72, v72
	v_exp_f32_e32 v73, v73
	v_pk_mul_f32 v[78:79], v[22:23], v[120:121] op_sel_hi:[1,0]
	v_pk_add_f32 v[70:71], v[70:71], 1.0 op_sel_hi:[1,0]
	v_pk_add_f32 v[72:73], v[72:73], 1.0 op_sel_hi:[1,0]
	v_rcp_f32_e32 v74, v70
	v_rcp_f32_e32 v75, v71
	v_rcp_f32_e32 v76, v72
	v_rcp_f32_e32 v77, v73
	v_pk_mul_f32 v[80:81], v[24:25], v[120:121] op_sel_hi:[1,0]
	v_pk_mul_f32 v[74:75], v[66:67], v[74:75]
	v_pk_mul_f32 v[76:77], v[68:69], v[76:77]
	v_pk_mul_f32 v[78:79], v[78:79], v[74:75]
	v_pk_mul_f32 v[80:81], v[80:81], v[76:77]
	v_cvt_pk_bf16_f32 v70, v78, v79
	v_cvt_pk_bf16_f32 v71, v80, v81
	global_store_dwordx2 v125, v[70:71], s[38:39] offset:64
	s_waitcnt vmcnt(15)
	v_lshlrev_b32_e32 v66, 16, v108
	v_and_b32_e32 v67, 0xffff0000, v108
	v_lshlrev_b32_e32 v68, 16, v109
	v_and_b32_e32 v69, 0xffff0000, v109
	v_mul_f32_e32 v70, 0xbfb8aa3b, v66
	v_mul_f32_e32 v71, 0xbfb8aa3b, v67
	v_mul_f32_e32 v72, 0xbfb8aa3b, v68
	v_mul_f32_e32 v73, 0xbfb8aa3b, v69
	v_exp_f32_e32 v70, v70
	v_exp_f32_e32 v71, v71
	v_exp_f32_e32 v72, v72
	v_exp_f32_e32 v73, v73
	v_pk_mul_f32 v[78:79], v[18:19], v[120:121] op_sel_hi:[1,0]
	v_pk_add_f32 v[70:71], v[70:71], 1.0 op_sel_hi:[1,0]
	v_pk_add_f32 v[72:73], v[72:73], 1.0 op_sel_hi:[1,0]
	v_rcp_f32_e32 v74, v70
	v_rcp_f32_e32 v75, v71
	v_rcp_f32_e32 v76, v72
	v_rcp_f32_e32 v77, v73
	v_pk_mul_f32 v[80:81], v[20:21], v[120:121] op_sel_hi:[1,0]
	v_pk_mul_f32 v[74:75], v[66:67], v[74:75]
	v_pk_mul_f32 v[76:77], v[68:69], v[76:77]
	v_pk_mul_f32 v[78:79], v[78:79], v[74:75]
	v_pk_mul_f32 v[80:81], v[80:81], v[76:77]
	v_cvt_pk_bf16_f32 v70, v78, v79
	v_cvt_pk_bf16_f32 v71, v80, v81
	global_store_dwordx2 v125, v[70:71], s[38:39] offset:96
	s_waitcnt vmcnt(15)
	v_lshlrev_b32_e32 v66, 16, v110
	v_and_b32_e32 v67, 0xffff0000, v110
	v_lshlrev_b32_e32 v68, 16, v111
	v_and_b32_e32 v69, 0xffff0000, v111
	v_mul_f32_e32 v70, 0xbfb8aa3b, v66
	v_mul_f32_e32 v71, 0xbfb8aa3b, v67
	v_mul_f32_e32 v72, 0xbfb8aa3b, v68
	v_mul_f32_e32 v73, 0xbfb8aa3b, v69
	v_exp_f32_e32 v70, v70
	v_exp_f32_e32 v71, v71
	v_exp_f32_e32 v72, v72
	v_exp_f32_e32 v73, v73
	v_pk_mul_f32 v[78:79], v[14:15], v[120:121] op_sel_hi:[1,0]
	v_pk_add_f32 v[70:71], v[70:71], 1.0 op_sel_hi:[1,0]
	v_pk_add_f32 v[72:73], v[72:73], 1.0 op_sel_hi:[1,0]
	v_rcp_f32_e32 v74, v70
	v_rcp_f32_e32 v75, v71
	v_rcp_f32_e32 v76, v72
	v_rcp_f32_e32 v77, v73
	v_pk_mul_f32 v[80:81], v[16:17], v[120:121] op_sel_hi:[1,0]
	v_pk_mul_f32 v[74:75], v[66:67], v[74:75]
	v_pk_mul_f32 v[76:77], v[68:69], v[76:77]
	v_pk_mul_f32 v[78:79], v[78:79], v[74:75]
	v_pk_mul_f32 v[80:81], v[80:81], v[76:77]
	v_cvt_pk_bf16_f32 v70, v78, v79
	v_cvt_pk_bf16_f32 v71, v80, v81
	global_store_dwordx2 v125, v[70:71], s[38:39] offset:128
	s_waitcnt vmcnt(15)
	v_lshlrev_b32_e32 v66, 16, v112
	v_and_b32_e32 v67, 0xffff0000, v112
	v_lshlrev_b32_e32 v68, 16, v113
	v_and_b32_e32 v69, 0xffff0000, v113
	v_mul_f32_e32 v70, 0xbfb8aa3b, v66
	v_mul_f32_e32 v71, 0xbfb8aa3b, v67
	v_mul_f32_e32 v72, 0xbfb8aa3b, v68
	v_mul_f32_e32 v73, 0xbfb8aa3b, v69
	v_exp_f32_e32 v70, v70
	v_exp_f32_e32 v71, v71
	v_exp_f32_e32 v72, v72
	v_exp_f32_e32 v73, v73
	v_pk_mul_f32 v[78:79], v[10:11], v[120:121] op_sel_hi:[1,0]
	v_pk_add_f32 v[70:71], v[70:71], 1.0 op_sel_hi:[1,0]
	v_pk_add_f32 v[72:73], v[72:73], 1.0 op_sel_hi:[1,0]
	v_rcp_f32_e32 v74, v70
	v_rcp_f32_e32 v75, v71
	v_rcp_f32_e32 v76, v72
	v_rcp_f32_e32 v77, v73
	v_pk_mul_f32 v[80:81], v[12:13], v[120:121] op_sel_hi:[1,0]
	v_pk_mul_f32 v[74:75], v[66:67], v[74:75]
	v_pk_mul_f32 v[76:77], v[68:69], v[76:77]
	v_pk_mul_f32 v[78:79], v[78:79], v[74:75]
	v_pk_mul_f32 v[80:81], v[80:81], v[76:77]
	v_cvt_pk_bf16_f32 v70, v78, v79
	v_cvt_pk_bf16_f32 v71, v80, v81
	global_store_dwordx2 v125, v[70:71], s[38:39] offset:160
	s_waitcnt vmcnt(15)
	v_lshlrev_b32_e32 v66, 16, v114
	v_and_b32_e32 v67, 0xffff0000, v114
	v_lshlrev_b32_e32 v68, 16, v115
	v_and_b32_e32 v69, 0xffff0000, v115
	v_mul_f32_e32 v70, 0xbfb8aa3b, v66
	v_mul_f32_e32 v71, 0xbfb8aa3b, v67
	v_mul_f32_e32 v72, 0xbfb8aa3b, v68
	v_mul_f32_e32 v73, 0xbfb8aa3b, v69
	v_exp_f32_e32 v70, v70
	v_exp_f32_e32 v71, v71
	v_exp_f32_e32 v72, v72
	v_exp_f32_e32 v73, v73
	v_pk_mul_f32 v[78:79], v[6:7], v[120:121] op_sel_hi:[1,0]
	v_pk_add_f32 v[70:71], v[70:71], 1.0 op_sel_hi:[1,0]
	v_pk_add_f32 v[72:73], v[72:73], 1.0 op_sel_hi:[1,0]
	v_rcp_f32_e32 v74, v70
	v_rcp_f32_e32 v75, v71
	v_rcp_f32_e32 v76, v72
	v_rcp_f32_e32 v77, v73
	v_pk_mul_f32 v[80:81], v[8:9], v[120:121] op_sel_hi:[1,0]
	v_pk_mul_f32 v[74:75], v[66:67], v[74:75]
	v_pk_mul_f32 v[76:77], v[68:69], v[76:77]
	v_pk_mul_f32 v[78:79], v[78:79], v[74:75]
	v_pk_mul_f32 v[80:81], v[80:81], v[76:77]
	v_cvt_pk_bf16_f32 v70, v78, v79
	v_cvt_pk_bf16_f32 v71, v80, v81
	global_store_dwordx2 v125, v[70:71], s[38:39] offset:192
	s_waitcnt vmcnt(15)
	v_lshlrev_b32_e32 v66, 16, v116
	v_and_b32_e32 v67, 0xffff0000, v116
	v_lshlrev_b32_e32 v68, 16, v117
	v_and_b32_e32 v69, 0xffff0000, v117
	v_mul_f32_e32 v70, 0xbfb8aa3b, v66
	v_mul_f32_e32 v71, 0xbfb8aa3b, v67
	v_mul_f32_e32 v72, 0xbfb8aa3b, v68
	v_mul_f32_e32 v73, 0xbfb8aa3b, v69
	v_exp_f32_e32 v70, v70
	v_exp_f32_e32 v71, v71
	v_exp_f32_e32 v72, v72
	v_exp_f32_e32 v73, v73
	v_pk_mul_f32 v[78:79], v[2:3], v[120:121] op_sel_hi:[1,0]
	v_pk_add_f32 v[70:71], v[70:71], 1.0 op_sel_hi:[1,0]
	v_pk_add_f32 v[72:73], v[72:73], 1.0 op_sel_hi:[1,0]
	v_rcp_f32_e32 v74, v70
	v_rcp_f32_e32 v75, v71
	v_rcp_f32_e32 v76, v72
	v_rcp_f32_e32 v77, v73
	v_pk_mul_f32 v[80:81], v[4:5], v[120:121] op_sel_hi:[1,0]
	v_pk_mul_f32 v[74:75], v[66:67], v[74:75]
	v_pk_mul_f32 v[76:77], v[68:69], v[76:77]
	v_pk_mul_f32 v[78:79], v[78:79], v[74:75]
	v_pk_mul_f32 v[80:81], v[80:81], v[76:77]
	v_cvt_pk_bf16_f32 v70, v78, v79
	v_cvt_pk_bf16_f32 v71, v80, v81
	global_store_dwordx2 v125, v[70:71], s[38:39] offset:224
	v_readlane_b32 s0, v236, 9
	s_add_i32 s40, s40, s0
	v_readlane_b32 s1, v236, 10
	s_cmpk_gt_i32 s40, 0xff
	s_cbranch_scc1 .LBB0_401

.LBB0_394:
	s_add_i32 s24, s24, -1
	s_add_i32 s41, s41, 64
	v_subrev_u32_e32 v227, 64, v227
	v_add_u32_e32 v228, 64, v228
	v_add_u32_e32 v229, 64, v229
	v_add_u32_e32 v230, 64, v230
	s_cmp_lt_u32 s25, 9
	v_add_u32_e32 v231, 64, v231
	s_waitcnt lgkmcnt(0)
	s_cbranch_scc0 .Lband_exit
	s_barrier
	v_mov_b32_e32 v233, v197
	v_mov_b32_e32 v232, v178
	s_cmp_lg_u32 s25, 8
	s_cselect_b64 s[18:19], -1, 0
	s_cmp_eq_u32 s25, 8
	s_cbranch_scc0 .LBB0_381
	s_branch .LBB0_382
.Lband_exit:
	v_mov_b32_e32 v138, v216
	v_lshlrev_b32_e32 v125, 1, v138
	v_mad_u32_u24 v122, v192, s59, v125
	v_lshl_add_u32 v124, v192, 12, v125
	s_add_u32 s14, s4, s0
	s_addc_u32 s15, s5, s1
	s_add_u32 s14, s14, 0x1000
	s_addc_u32 s15, s15, 0
	s_add_u32 s38, s56, s0
	s_addc_u32 s39, s57, s1
	v_add_u32_e32 v123, 0x2a000, v122
	v_add_u32_e32 v125, 0x10000, v124
	global_load_dwordx2 v[86:87], v122, s[14:15] nt
	global_load_dwordx2 v[88:89], v122, s[14:15] offset:32 nt
	global_load_dwordx2 v[90:91], v122, s[14:15] offset:64 nt
	global_load_dwordx2 v[92:93], v122, s[14:15] offset:96 nt
	global_load_dwordx2 v[94:95], v122, s[14:15] offset:128 nt
	global_load_dwordx2 v[96:97], v122, s[14:15] offset:160 nt
	global_load_dwordx2 v[98:99], v122, s[14:15] offset:192 nt
	global_load_dwordx2 v[100:101], v122, s[14:15] offset:224 nt
	global_load_dwordx2 v[102:103], v123, s[14:15] nt
	global_load_dwordx2 v[104:105], v123, s[14:15] offset:32 nt
	global_load_dwordx2 v[106:107], v123, s[14:15] offset:64 nt
	global_load_dwordx2 v[108:109], v123, s[14:15] offset:96 nt
	global_load_dwordx2 v[110:111], v123, s[14:15] offset:128 nt
	global_load_dwordx2 v[112:113], v123, s[14:15] offset:160 nt
	global_load_dwordx2 v[114:115], v123, s[14:15] offset:192 nt
	global_load_dwordx2 v[116:117], v123, s[14:15] offset:224 nt
	s_barrier
	s_branch .Lband_epi_compute
